# combined: convT LDS reads batched, hynorm gain load batched, MLP weight staging batched, gla_out gate-loop q/k copies moved to the iteration end
# speedup vs baseline: 1.0002x; 1.0002x over previous
.Lmy_cw_cached:
	v_mov_b32_e32 v18, v247
	v_mov_b32_e32 v48, v248
	v_mov_b32_e32 v50, v249
	s_waitcnt lgkmcnt(0)
	s_barrier
	ds_read_u16 v94, v77 offset:41728
	ds_read_u16 v95, v77 offset:41856
	ds_read_u16 v96, v77 offset:42112
	ds_read_u16 v97, v77 offset:41984
	ds_read_u16 v98, v77 offset:50176
	ds_read_u16 v99, v77 offset:50304
	ds_read_u16 v100, v77 offset:50560
	ds_read_u16 v101, v77 offset:50432
	ds_read_u16 v102, v77 offset:33280
	ds_read_u16 v103, v78 offset:33280
	ds_read_u16 v104, v77 offset:33664
	ds_read_u16 v105, v79 offset:33280
	ds_read_u16 v106, v77 offset:42240
	ds_read_u16 v107, v77 offset:42368
	ds_read_u16 v108, v77 offset:50688
	ds_read_u16 v109, v77 offset:50816
	ds_read_u16 v110, v77 offset:33792
	ds_read_u16 v111, v77 offset:33920
	ds_read_u16 v112, v77 offset:42624
	ds_read_u16 v113, v77 offset:42496
	ds_read_u16 v114, v77 offset:51072
	ds_read_u16 v115, v77 offset:50944
	ds_read_u16 v116, v80 offset:33280
	ds_read_u16 v117, v77 offset:34048
	ds_read_u16 v118, v77 offset:34304
	ds_read_u16 v119, v77 offset:42752
	ds_read_u16 v120, v77 offset:51200
	ds_read_u16 v121, v81 offset:33280
	ds_read_u16 v122, v81 offset:33408
	ds_read_u16 v123, v81 offset:33536
	ds_read_u16 v124, v81 offset:41728
	ds_read_u16 v125, v81 offset:41856
	ds_read_u16 v126, v81 offset:41984
	ds_read_u16 v127, v81 offset:50176
	ds_read_u16 v128, v81 offset:50304
	ds_read_u16 v129, v81 offset:50432
	s_waitcnt lgkmcnt(0)
	s_ashr_i32 s29, s28, 31
	s_andn2_b64 vcc, exec, s[26:27]
	v_readlane_b32 s53, v253, 8
	s_waitcnt lgkmcnt(1)
	v_lshlrev_b32_e32 v82, 16, v94
	v_readlane_b32 s54, v253, 9
	v_readlane_b32 s55, v253, 10
	v_readlane_b32 s56, v253, 11
	s_waitcnt lgkmcnt(1)
	v_lshlrev_b32_e32 v85, 16, v96
	s_waitcnt lgkmcnt(0)
	v_lshlrev_b32_e32 v84, 16, v97
	v_lshlrev_b32_e32 v83, 16, v95
	v_mov_b32_e32 v86, v83
	v_mov_b32_e32 v87, v84
	v_readlane_b32 s57, v253, 12
	s_waitcnt lgkmcnt(1)
	v_lshlrev_b32_e32 v88, 16, v98
	v_readlane_b32 s58, v253, 13
	v_readlane_b32 s59, v253, 14
	v_readlane_b32 s60, v253, 15
	s_waitcnt lgkmcnt(1)
	v_lshlrev_b32_e32 v91, 16, v100
	s_waitcnt lgkmcnt(0)
	v_lshlrev_b32_e32 v90, 16, v101
	v_lshlrev_b32_e32 v89, 16, v99
	v_mov_b32_e32 v92, v89
	v_mov_b32_e32 v93, v90
	v_readlane_b32 s61, v253, 16
	v_readlane_b32 s62, v253, 17
	v_readlane_b32 s63, v253, 18
	v_readlane_b32 s64, v253, 19
	v_readlane_b32 s65, v253, 20
	v_pk_fma_f32 v[82:83], v[62:63], v[82:83], v[48:49] op_sel_hi:[0,1,0]
	v_pk_fma_f32 v[82:83], v[60:61], v[86:87], v[82:83] op_sel_hi:[0,1,1]
	v_pk_fma_f32 v[82:83], v[58:59], v[84:85], v[82:83] op_sel_hi:[0,1,1]
	v_pk_fma_f32 v[86:87], v[56:57], v[88:89], v[50:51] op_sel_hi:[0,1,0]
	v_pk_fma_f32 v[86:87], v[54:55], v[92:93], v[86:87] op_sel_hi:[0,1,1]
	v_pk_fma_f32 v[86:87], v[52:53], v[90:91], v[86:87] op_sel_hi:[0,1,1]
	v_pk_mul_f32 v[82:83], v[82:83], v[86:87]
	ds_write2_b32 v59, v82, v83 offset1:1
	s_waitcnt lgkmcnt(1)
	v_lshlrev_b32_e32 v82, 16, v102
	s_waitcnt lgkmcnt(1)
	v_lshlrev_b32_e32 v87, 16, v104
	s_waitcnt lgkmcnt(0)
	v_lshlrev_b32_e32 v86, 16, v105
	v_lshlrev_b32_e32 v83, 16, v103
	v_mov_b32_e32 v88, v83
	v_mov_b32_e32 v89, v86
	v_pk_fma_f32 v[82:83], v[68:69], v[82:83], v[18:19] op_sel_hi:[0,1,0]
	v_pk_fma_f32 v[82:83], v[66:67], v[88:89], v[82:83] op_sel_hi:[0,1,1]
	v_pk_fma_f32 v[82:83], v[64:65], v[86:87], v[82:83] op_sel_hi:[0,1,1]
	v_add_u32_e32 v17, 0x4100, v59
	ds_write2_b32 v17, v82, v83 offset1:1
	v_pk_fma_f32 v[82:83], v[62:63], v[84:85], v[48:49] op_sel_hi:[0,1,0]
	s_waitcnt lgkmcnt(1)
	v_lshlrev_b32_e32 v88, 16, v106
	s_waitcnt lgkmcnt(0)
	v_lshlrev_b32_e32 v89, 16, v107
	v_pk_mov_b32 v[84:85], v[84:85], v[88:89] op_sel:[1,0]
	s_waitcnt lgkmcnt(1)
	v_lshlrev_b32_e32 v92, 16, v108
	s_waitcnt lgkmcnt(0)
	v_lshlrev_b32_e32 v93, 16, v109
	v_pk_fma_f32 v[82:83], v[60:61], v[84:85], v[82:83] op_sel_hi:[0,1,1]
	v_pk_fma_f32 v[84:85], v[56:57], v[90:91], v[50:51] op_sel_hi:[0,1,0]
	v_pk_mov_b32 v[90:91], v[90:91], v[92:93] op_sel:[1,0]
	v_pk_fma_f32 v[82:83], v[58:59], v[88:89], v[82:83] op_sel_hi:[0,1,1]
	v_pk_fma_f32 v[84:85], v[54:55], v[90:91], v[84:85] op_sel_hi:[0,1,1]
	v_pk_fma_f32 v[84:85], v[52:53], v[92:93], v[84:85] op_sel_hi:[0,1,1]
	v_pk_mul_f32 v[82:83], v[82:83], v[84:85]
	s_waitcnt lgkmcnt(0)
	v_lshlrev_b32_e32 v85, 16, v111
	v_lshlrev_b32_e32 v84, 16, v110
	ds_write2_b32 v59, v82, v83 offset0:2 offset1:3
	v_pk_fma_f32 v[82:83], v[68:69], v[86:87], v[18:19] op_sel_hi:[0,1,0]
	v_pk_mov_b32 v[86:87], v[86:87], v[84:85] op_sel:[1,0]
	v_add_u32_e32 v17, 0x4108, v59
	v_pk_fma_f32 v[82:83], v[66:67], v[86:87], v[82:83] op_sel_hi:[0,1,1]
	v_pk_fma_f32 v[82:83], v[64:65], v[84:85], v[82:83] op_sel_hi:[0,1,1]
	ds_write2_b32 v17, v82, v83 offset1:1
	v_pk_fma_f32 v[82:83], v[62:63], v[88:89], v[48:49] op_sel_hi:[0,1,0]
	s_waitcnt lgkmcnt(1)
	v_lshlrev_b32_e32 v87, 16, v112
	s_waitcnt lgkmcnt(0)
	v_lshlrev_b32_e32 v86, 16, v113
	v_pk_mov_b32 v[88:89], v[88:89], v[86:87] op_sel:[1,0]
	s_waitcnt lgkmcnt(1)
	v_lshlrev_b32_e32 v91, 16, v114
	s_waitcnt lgkmcnt(0)
	v_lshlrev_b32_e32 v90, 16, v115
	v_pk_fma_f32 v[82:83], v[60:61], v[88:89], v[82:83] op_sel_hi:[0,1,1]
	v_pk_fma_f32 v[88:89], v[56:57], v[92:93], v[50:51] op_sel_hi:[0,1,0]
	v_pk_mov_b32 v[92:93], v[92:93], v[90:91] op_sel:[1,0]
	v_pk_fma_f32 v[82:83], v[58:59], v[86:87], v[82:83] op_sel_hi:[0,1,1]
	v_pk_fma_f32 v[88:89], v[54:55], v[92:93], v[88:89] op_sel_hi:[0,1,1]
	v_pk_fma_f32 v[88:89], v[52:53], v[90:91], v[88:89] op_sel_hi:[0,1,1]
	v_pk_mul_f32 v[82:83], v[82:83], v[88:89]
	ds_write2_b32 v59, v82, v83 offset0:4 offset1:5
	v_pk_fma_f32 v[82:83], v[68:69], v[84:85], v[18:19] op_sel_hi:[0,1,0]
	s_waitcnt lgkmcnt(1)
	v_lshlrev_b32_e32 v89, 16, v116
	s_waitcnt lgkmcnt(0)
	v_lshlrev_b32_e32 v88, 16, v117
	v_pk_mov_b32 v[84:85], v[84:85], v[88:89] op_sel:[1,0]
	v_pk_fma_f32 v[82:83], v[66:67], v[84:85], v[82:83] op_sel_hi:[0,1,1]
	v_pk_fma_f32 v[82:83], v[64:65], v[88:89], v[82:83] op_sel_hi:[0,1,1]
	v_add_u32_e32 v17, 0x4110, v59
	ds_write2_b32 v17, v82, v83 offset1:1
	v_fma_f32 v17, v68, v88, v18
	v_fmac_f32_e32 v17, v66, v89
	s_waitcnt lgkmcnt(3)
	v_lshlrev_b32_e32 v19, 16, v118
	v_fmac_f32_e32 v17, v64, v19
	v_fma_f32 v19, v62, v86, v48
	v_fmac_f32_e32 v19, v60, v87
	s_waitcnt lgkmcnt(1)
	v_lshlrev_b32_e32 v82, 16, v119
	v_fmac_f32_e32 v19, v58, v82
	v_fma_f32 v82, v56, v90, v50
	v_fmac_f32_e32 v82, v54, v91
	s_waitcnt lgkmcnt(0)
	v_lshlrev_b32_e32 v83, 16, v120
	v_fmac_f32_e32 v82, v52, v83
	v_mul_f32_e32 v19, v19, v82
	v_add_u32_e32 v82, 24, v59
	ds_write2st64_b32 v82, v19, v17 offset1:65
	v_add_u32_e32 v84, s2, v53
	v_ashrrev_i32_e32 v85, 31, v84
	v_mov_b32_e32 v19, s29
	v_lshlrev_b64 v[84:85], 13, v[84:85]
	s_waitcnt lgkmcnt(0)
	v_lshlrev_b32_e32 v17, 16, v121
	v_fmac_f32_e32 v18, v68, v17
	s_waitcnt lgkmcnt(0)
	v_lshlrev_b32_e32 v17, 16, v122
	v_fmac_f32_e32 v18, v66, v17
	s_waitcnt lgkmcnt(0)
	v_lshlrev_b32_e32 v17, 16, v123
	v_fmac_f32_e32 v18, v64, v17
	s_waitcnt lgkmcnt(0)
	v_lshlrev_b32_e32 v17, 16, v124
	v_fmac_f32_e32 v48, v62, v17
	s_waitcnt lgkmcnt(0)
	v_lshlrev_b32_e32 v17, 16, v125
	v_fmac_f32_e32 v48, v60, v17
	s_waitcnt lgkmcnt(0)
	v_lshlrev_b32_e32 v17, 16, v126
	v_fmac_f32_e32 v48, v58, v17
	s_waitcnt lgkmcnt(0)
	v_lshlrev_b32_e32 v17, 16, v127
	v_fmac_f32_e32 v50, v56, v17
	s_waitcnt lgkmcnt(0)
	v_lshlrev_b32_e32 v17, 16, v128
	v_fmac_f32_e32 v50, v54, v17
	s_waitcnt lgkmcnt(0)
	v_lshlrev_b32_e32 v17, 16, v129
	v_fmac_f32_e32 v50, v52, v17
	v_mul_f32_e32 v17, v48, v50
	ds_write2st64_b32 v70, v17, v18 offset1:65
	s_waitcnt lgkmcnt(0)
	s_barrier
	ds_read2_b32 v[82:83], v71 offset1:65
	v_or_b32_e32 v18, s28, v46
	v_lshl_add_u64 v[84:85], v[84:85], 0, v[18:19]
	v_lshlrev_b64 v[84:85], 1, v[84:85]
	v_lshl_add_u64 v[86:87], s[16:17], 0, v[84:85]
	s_waitcnt lgkmcnt(0)
	v_bfe_u32 v17, v82, 16, 1
	v_add3_u32 v17, v82, v17, s33
	s_waitcnt vmcnt(0)
	global_store_short_d16_hi v[86:87], v17, off
	v_add_u32_e32 v17, 0x4000, v71
	ds_read2_b32 v[86:87], v17 offset0:64 offset1:129
	v_lshl_add_u64 v[84:85], s[0:1], 0, v[84:85]
	v_add_u32_e32 v82, s2, v55
	s_waitcnt lgkmcnt(0)
	v_bfe_u32 v17, v86, 16, 1
	v_add3_u32 v17, v86, v17, s33
	global_store_short_d16_hi v[84:85], v17, off
	v_bfe_u32 v17, v83, 16, 1
	v_add3_u32 v17, v83, v17, s33
	v_ashrrev_i32_e32 v83, 31, v82
	v_lshlrev_b64 v[82:83], 13, v[82:83]
	v_lshl_add_u64 v[82:83], v[82:83], 0, v[18:19]
	v_lshlrev_b64 v[82:83], 1, v[82:83]
	v_lshl_add_u64 v[84:85], s[16:17], 0, v[82:83]
	global_store_short_d16_hi v[84:85], v17, off
	v_bfe_u32 v17, v87, 16, 1
	v_add3_u32 v17, v87, v17, s33
	v_lshl_add_u64 v[82:83], s[0:1], 0, v[82:83]
	global_store_short_d16_hi v[82:83], v17, off
	ds_read2_b32 v[82:83], v71 offset0:130 offset1:195
	v_add_u32_e32 v84, s2, v57
	v_ashrrev_i32_e32 v85, 31, v84
	v_lshlrev_b64 v[84:85], 13, v[84:85]
	v_lshl_add_u64 v[84:85], v[84:85], 0, v[18:19]
	s_waitcnt lgkmcnt(0)
	v_bfe_u32 v17, v82, 16, 1
	v_lshlrev_b64 v[84:85], 1, v[84:85]
	v_add3_u32 v17, v82, v17, s33
	v_lshl_add_u64 v[86:87], s[16:17], 0, v[84:85]
	global_store_short_d16_hi v[86:87], v17, off
	v_add_u32_e32 v17, 0x4200, v71
	ds_read2_b32 v[86:87], v17 offset0:66 offset1:131
	v_lshl_add_u64 v[84:85], s[0:1], 0, v[84:85]
	v_add_u32_e32 v82, s2, v61
	s_waitcnt lgkmcnt(0)
	v_bfe_u32 v17, v86, 16, 1
	v_add3_u32 v17, v86, v17, s33
	global_store_short_d16_hi v[84:85], v17, off
	v_bfe_u32 v17, v83, 16, 1
	v_add3_u32 v17, v83, v17, s33
	v_ashrrev_i32_e32 v83, 31, v82
	v_lshlrev_b64 v[82:83], 13, v[82:83]
	v_lshl_add_u64 v[82:83], v[82:83], 0, v[18:19]
	v_lshlrev_b64 v[82:83], 1, v[82:83]
	v_lshl_add_u64 v[84:85], s[16:17], 0, v[82:83]
	global_store_short_d16_hi v[84:85], v17, off
	v_bfe_u32 v17, v87, 16, 1
	v_add3_u32 v17, v87, v17, s33
	v_lshl_add_u64 v[82:83], s[0:1], 0, v[82:83]
	global_store_short_d16_hi v[82:83], v17, off
	v_add_u32_e32 v17, 0x400, v71
	ds_read2_b32 v[82:83], v17 offset0:4 offset1:69
	v_add_u32_e32 v84, s2, v63
	v_ashrrev_i32_e32 v85, 31, v84
	v_lshlrev_b64 v[84:85], 13, v[84:85]
	v_lshl_add_u64 v[84:85], v[84:85], 0, v[18:19]
	s_waitcnt lgkmcnt(0)
	v_bfe_u32 v17, v82, 16, 1
	v_lshlrev_b64 v[84:85], 1, v[84:85]
	v_add3_u32 v17, v82, v17, s33
	v_lshl_add_u64 v[86:87], s[16:17], 0, v[84:85]
	global_store_short_d16_hi v[86:87], v17, off
	v_add_u32_e32 v17, 0x4400, v71
	ds_read2_b32 v[86:87], v17 offset0:68 offset1:133
	v_lshl_add_u64 v[84:85], s[0:1], 0, v[84:85]
	v_add_u32_e32 v82, s2, v65
	s_waitcnt lgkmcnt(0)
	v_bfe_u32 v17, v86, 16, 1
	v_add3_u32 v17, v86, v17, s33
	global_store_short_d16_hi v[84:85], v17, off
	v_bfe_u32 v17, v83, 16, 1
	v_add3_u32 v17, v83, v17, s33
	v_ashrrev_i32_e32 v83, 31, v82
	v_lshlrev_b64 v[82:83], 13, v[82:83]
	v_lshl_add_u64 v[82:83], v[82:83], 0, v[18:19]
	v_lshlrev_b64 v[82:83], 1, v[82:83]
	v_lshl_add_u64 v[84:85], s[16:17], 0, v[82:83]
	global_store_short_d16_hi v[84:85], v17, off
	v_bfe_u32 v17, v87, 16, 1
	v_add3_u32 v17, v87, v17, s33
	v_lshl_add_u64 v[82:83], s[0:1], 0, v[82:83]
	global_store_short_d16_hi v[82:83], v17, off
	ds_read_b32 v17, v71 offset:1560
	v_add_u32_e32 v82, s2, v67
	v_ashrrev_i32_e32 v83, 31, v82
	v_lshlrev_b64 v[82:83], 13, v[82:83]
	v_lshl_add_u64 v[82:83], v[82:83], 0, v[18:19]
	s_waitcnt lgkmcnt(0)
	v_bfe_u32 v48, v17, 16, 1
	v_lshlrev_b64 v[82:83], 1, v[82:83]
	v_add3_u32 v17, v17, v48, s33
	v_lshl_add_u64 v[84:85], s[16:17], 0, v[82:83]
	global_store_short_d16_hi v[84:85], v17, off
	ds_read_b32 v17, v71 offset:18200
	v_lshl_add_u64 v[82:83], s[0:1], 0, v[82:83]
	v_add_u32_e32 v84, s2, v69
	v_ashrrev_i32_e32 v85, 31, v84
	v_lshlrev_b64 v[84:85], 13, v[84:85]
	s_waitcnt lgkmcnt(0)
	v_bfe_u32 v48, v17, 16, 1
	v_add3_u32 v17, v17, v48, s33
	global_store_short_d16_hi v[82:83], v17, off
	ds_read2st64_b32 v[82:83], v72 offset1:65
	v_lshl_add_u64 v[18:19], v[84:85], 0, v[18:19]
	v_lshlrev_b64 v[18:19], 1, v[18:19]
	v_lshl_add_u64 v[84:85], s[16:17], 0, v[18:19]
	v_lshl_add_u64 v[18:19], s[0:1], 0, v[18:19]
	s_waitcnt lgkmcnt(0)
	v_bfe_u32 v17, v82, 16, 1
	v_add3_u32 v17, v82, v17, s33
	global_store_short_d16_hi v[84:85], v17, off
	v_bfe_u32 v17, v83, 16, 1
	v_add3_u32 v17, v83, v17, s33
	global_store_short_d16_hi v[18:19], v17, off
	s_barrier
	s_cbranch_vccnz .LBB0_528
	v_mov_b64_e32 v[8:9], v[32:33]
	v_mov_b64_e32 v[12:13], v[28:29]
	v_mov_b64_e32 v[0:1], v[20:21]
	v_mov_b64_e32 v[4:5], v[24:25]
	v_mov_b64_e32 v[10:11], v[34:35]
	v_mov_b64_e32 v[14:15], v[30:31]
	v_mov_b64_e32 v[2:3], v[22:23]
	v_mov_b64_e32 v[6:7], v[26:27]
	s_branch .LBB0_528

.LBB0_764:
	v_and_or_b32 v40, s0, 24, v147
	v_add_u32_e32 v45, s0, v147
	v_add_u32_e32 v43, 7, v21
	s_waitcnt vmcnt(15)
	v_lshlrev_b32_e32 v47, 16, v36
	s_waitcnt vmcnt(13)
	v_lshlrev_b32_e32 v48, 16, v34
	s_waitcnt vmcnt(11)
	v_lshlrev_b32_e32 v32, 16, v32
	s_waitcnt vmcnt(9)
	v_lshlrev_b32_e32 v30, 16, v30
	s_waitcnt vmcnt(7)
	v_lshlrev_b32_e32 v28, 16, v28
	s_waitcnt vmcnt(5)
	v_lshlrev_b32_e32 v26, 16, v26
	s_waitcnt vmcnt(3)
	v_lshlrev_b32_e32 v24, 16, v24
	s_waitcnt vmcnt(2)
	v_lshlrev_b32_e32 v44, 16, v25
	s_waitcnt vmcnt(1)
	v_lshlrev_b32_e32 v22, 16, v22
	s_waitcnt vmcnt(0)
	v_lshlrev_b32_e32 v46, 16, v23
	v_sub_u32_e32 v23, 63, v40
	v_or_b32_e32 v25, 1, v40
	v_or_b32_e32 v49, 2, v40
	v_or_b32_e32 v50, 3, v40
	v_or_b32_e32 v51, 4, v40
	v_or_b32_e32 v54, 5, v40
	v_or_b32_e32 v55, 6, v40
	v_or_b32_e32 v157, 7, v40
	v_add_u32_e32 v52, -8, v45
	v_lshlrev_b32_e32 v36, 16, v37
	v_add_u32_e32 v37, 6, v21
	v_lshlrev_b32_e32 v38, 16, v33
	v_add_u32_e32 v33, 4, v21
	v_lshlrev_b32_e32 v39, 16, v31
	v_add_u32_e32 v31, 3, v21
	v_lshlrev_b32_e32 v41, 16, v29
	v_add_u32_e32 v29, 2, v21
	v_lshlrev_b32_e32 v42, 16, v27
	v_add_u32_e32 v27, 1, v21
	v_mul_f32_e32 v189, 0x3db504f3, v47
	v_add_u32_e32 v53, -7, v45
	v_mul_f32_e32 v218, 0x3db504f3, v48
	v_add_u32_e32 v48, -6, v45
	v_mul_f32_e32 v219, 0x3db504f3, v32
	v_add_u32_e32 v32, -5, v45
	v_mul_f32_e32 v220, 0x3db504f3, v30
	v_add_u32_e32 v30, -4, v45
	v_mul_f32_e32 v221, 0x3db504f3, v28
	v_add_u32_e32 v28, -3, v45
	v_mul_f32_e32 v222, 0x3db504f3, v26
	v_add_u32_e32 v26, -2, v45
	v_mul_f32_e32 v47, 0x3db504f3, v24
	v_add_u32_e32 v24, -1, v45
	v_mul_f32_e32 v45, 0x3db504f3, v22
	v_cndmask_b32_e64 v22, v23, v40, s[4:5]
	v_sub_u32_e32 v23, 63, v25
	v_sub_u32_e32 v40, 63, v49
	v_sub_u32_e32 v190, 63, v50
	v_sub_u32_e32 v191, 63, v51
	v_sub_u32_e32 v192, 63, v54
	v_sub_u32_e32 v193, 63, v55
	v_sub_u32_e32 v194, 63, v157
	v_cndmask_b32_e64 v43, v43, v52, s[4:5]
	v_lshlrev_b32_e32 v34, 16, v35
	v_add_u32_e32 v35, 5, v21
	v_cndmask_b32_e64 v37, v37, v53, s[4:5]
	v_cndmask_b32_e64 v32, v33, v32, s[4:5]
	v_cndmask_b32_e64 v30, v31, v30, s[4:5]
	v_cndmask_b32_e64 v28, v29, v28, s[4:5]
	v_cndmask_b32_e64 v26, v27, v26, s[4:5]
	v_cndmask_b32_e64 v24, v21, v24, s[4:5]
	v_mad_i64_i32 v[52:53], s[10:11], v22, s15, v[18:19]
	v_cndmask_b32_e64 v22, v23, v25, s[4:5]
	v_cndmask_b32_e64 v23, v40, v49, s[4:5]
	v_cndmask_b32_e64 v25, v190, v50, s[4:5]
	v_cndmask_b32_e64 v27, v191, v51, s[4:5]
	v_cndmask_b32_e64 v29, v192, v54, s[4:5]
	v_cndmask_b32_e64 v31, v193, v55, s[4:5]
	v_cndmask_b32_e64 v33, v194, v157, s[4:5]
	v_lshl_add_u32 v40, v43, 7, v164
	v_cndmask_b32_e64 v35, v35, v48, s[4:5]
	v_add_u32_e32 v157, v43, v163
	v_lshl_add_u32 v225, v32, 7, v164
	v_add_u32_e32 v208, v32, v163
	v_lshl_add_u32 v226, v30, 7, v164
	v_add_u32_e32 v210, v30, v163
	v_lshl_add_u32 v227, v28, 7, v164
	v_add_u32_e32 v212, v28, v163
	v_lshl_add_u32 v228, v26, 7, v164
	v_add_u32_e32 v214, v26, v163
	v_lshl_add_u32 v43, v24, 7, v164
	v_add_u32_e32 v216, v24, v163
	v_mad_i64_i32 v[54:55], s[10:11], v22, s15, v[18:19]
	v_mad_i64_i32 v[190:191], s[10:11], v23, s15, v[18:19]
	v_mad_i64_i32 v[192:193], s[10:11], v25, s15, v[18:19]
	v_mad_i64_i32 v[194:195], s[10:11], v27, s15, v[18:19]
	v_mad_i64_i32 v[196:197], s[10:11], v29, s15, v[18:19]
	v_mad_i64_i32 v[198:199], s[10:11], v31, s15, v[18:19]
	v_mad_i64_i32 v[200:201], s[10:11], v33, s15, v[18:19]
	ds_read_b128 v[22:25], v40
	ds_read_b128 v[26:29], v40 offset:16
	ds_read_b128 v[30:33], v40 offset:32
	ds_read_b128 v[48:51], v40 offset:48
	v_lshl_add_u32 v223, v37, 7, v164
	v_add_u32_e32 v37, v37, v163
	v_lshl_add_u32 v224, v35, 7, v164
	v_add_u32_e32 v35, v35, v163
	v_mad_u64_u32 v[202:203], s[10:11], v157, s39, v[124:125]
	v_mad_u64_u32 v[204:205], s[10:11], v37, s39, v[124:125]
	v_mad_u64_u32 v[206:207], s[10:11], v35, s39, v[124:125]
	global_load_ushort v229, v[52:53], off
	global_load_ushort v230, v[52:53], off offset:1024
	global_load_ushort v231, v[54:55], off
	global_load_ushort v232, v[54:55], off offset:1024
	global_load_ushort v233, v[190:191], off
	s_nop 0
	global_load_ushort v234, v[190:191], off offset:1024
	s_nop 0
	global_load_ushort v235, v[192:193], off
	s_nop 0
	global_load_ushort v236, v[192:193], off offset:1024
	s_nop 0
	global_load_ushort v237, v[194:195], off
	s_nop 0
	global_load_ushort v238, v[194:195], off offset:1024
	s_nop 0
	global_load_ushort v239, v[196:197], off
	s_nop 0
	global_load_ushort v240, v[196:197], off offset:1024
	s_nop 0
	global_load_ushort v241, v[198:199], off
	s_nop 0
	global_load_ushort v242, v[198:199], off offset:1024
	s_nop 0
	global_load_ushort v243, v[200:201], off
	s_nop 0
	global_load_ushort v244, v[200:201], off offset:1024
	s_waitcnt lgkmcnt(3)
	v_mov_b32_e32 v52, v22
	s_waitcnt lgkmcnt(1)
	v_mov_b32_e32 v53, v30
	v_mov_b32_e32 v54, v26
	s_waitcnt lgkmcnt(0)
	v_mov_b32_e32 v55, v48
	v_mov_b32_e32 v30, v23
	v_mov_b32_e32 v48, v27
	v_mov_b32_e32 v22, v24
	v_mov_b32_e32 v23, v32
	v_mov_b32_e32 v26, v28
	v_mov_b32_e32 v27, v50
	v_mov_b32_e32 v32, v25
	v_mov_b32_e32 v50, v29
	v_pk_fma_f32 v[24:25], v[0:1], v[52:53], v[16:17]
	v_pk_fma_f32 v[28:29], v[8:9], v[54:55], 0 op_sel_hi:[1,1,0]
	v_pk_fma_f32 v[24:25], v[2:3], v[30:31], v[24:25]
	v_pk_fma_f32 v[28:29], v[10:11], v[48:49], v[28:29]
	v_pk_fma_f32 v[22:23], v[4:5], v[22:23], v[24:25]
	v_pk_fma_f32 v[24:25], v[12:13], v[26:27], v[28:29]
	v_pk_fma_f32 v[22:23], v[6:7], v[32:33], v[22:23]
	v_pk_fma_f32 v[24:25], v[14:15], v[50:51], v[24:25]
	v_lshl_add_u32 v37, v202, 1, 0
	v_pk_add_f32 v[22:23], v[22:23], v[24:25]
	v_lshl_add_u32 v201, v204, 1, 0
	v_add_f32_e32 v22, v22, v23
	v_min_f32_e32 v23, 0, v22
	v_mul_f32_e64 v22, |v22|, s33
	v_exp_f32_e32 v22, v22
	v_lshl_add_u32 v202, v206, 1, 0
	v_mad_u64_u32 v[208:209], s[10:11], v208, s39, v[124:125]
	v_add_f32_e32 v22, 1.0, v22
	v_cmp_gt_f32_e32 vcc, s35, v22
	v_lshl_add_u32 v204, v208, 1, 0
	v_mad_u64_u32 v[210:211], s[10:11], v210, s39, v[124:125]
	v_cndmask_b32_e64 v24, 0, 32, vcc
	v_ldexp_f32 v22, v22, v24
	v_log_f32_e32 v22, v22
	v_cndmask_b32_e32 v24, 0, v186, vcc
	v_lshl_add_u32 v206, v210, 1, 0
	v_mad_u64_u32 v[212:213], s[10:11], v212, s39, v[124:125]
	v_mul_f32_e32 v25, 0x3f317217, v22
	v_fma_f32 v25, v22, s36, -v25
	v_fmac_f32_e32 v25, 0x3377d1cf, v22
	v_fmac_f32_e32 v25, 0x3f317217, v22
	v_cmp_lt_f32_e64 vcc, |v22|, s37
	v_lshl_add_u32 v208, v212, 1, 0
	v_mad_u64_u32 v[214:215], s[10:11], v214, s39, v[124:125]
	v_cndmask_b32_e32 v22, v22, v25, vcc
	v_sub_f32_e32 v22, v22, v24
	v_sub_f32_e32 v22, v23, v22
	v_fmac_f32_e32 v20, 0x3d800000, v22
	v_mul_f32_e32 v22, 0x3fb8aa3b, v20
	v_mul_f32_e32 v23, 0xbfb8aa3b, v20
	v_exp_f32_e32 v22, v22
	v_exp_f32_e32 v23, v23
	v_lshl_add_u32 v209, v214, 1, 0
	s_add_i32 s0, s0, 8
	v_mul_f32_e32 v22, v189, v22
	v_mul_f32_e32 v23, v23, v36
	v_bfe_u32 v24, v22, 16, 1
	v_bfe_u32 v25, v23, 16, 1
	v_add3_u32 v22, v22, v24, s38
	v_add3_u32 v23, v23, v25, s38
	ds_write_b16_d16_hi v37, v22
	ds_write_b16_d16_hi v37, v23 offset:34816
	ds_read_b128 v[22:25], v223
	ds_read_b128 v[26:29], v223 offset:32
	ds_read_b128 v[30:33], v223 offset:16
	ds_read_b128 v[48:51], v223 offset:48
	v_mad_u64_u32 v[216:217], s[10:11], v216, s39, v[124:125]
	s_waitcnt lgkmcnt(3)
	v_mov_b32_e32 v36, v22
	s_waitcnt lgkmcnt(2)
	v_mov_b32_e32 v37, v26
	s_waitcnt lgkmcnt(1)
	v_mov_b32_e32 v52, v30
	s_waitcnt lgkmcnt(0)
	v_mov_b32_e32 v53, v48
	v_mov_b32_e32 v26, v23
	v_mov_b32_e32 v48, v31
	v_mov_b32_e32 v22, v24
	v_mov_b32_e32 v23, v28
	v_mov_b32_e32 v30, v32
	v_mov_b32_e32 v31, v50
	v_mov_b32_e32 v28, v25
	v_mov_b32_e32 v50, v33
	v_pk_fma_f32 v[24:25], v[0:1], v[36:37], v[16:17]
	v_pk_fma_f32 v[32:33], v[8:9], v[52:53], 0 op_sel_hi:[1,1,0]
	v_pk_fma_f32 v[24:25], v[2:3], v[26:27], v[24:25]
	v_pk_fma_f32 v[26:27], v[10:11], v[48:49], v[32:33]
	v_pk_fma_f32 v[22:23], v[4:5], v[22:23], v[24:25]
	v_pk_fma_f32 v[24:25], v[12:13], v[30:31], v[26:27]
	v_pk_fma_f32 v[22:23], v[6:7], v[28:29], v[22:23]
	v_pk_fma_f32 v[24:25], v[14:15], v[50:51], v[24:25]
	s_nop 0
	v_pk_add_f32 v[22:23], v[22:23], v[24:25]
	s_nop 0
	v_add_f32_e32 v22, v22, v23
	v_min_f32_e32 v23, 0, v22
	v_mul_f32_e64 v22, |v22|, s33
	v_exp_f32_e32 v22, v22
	s_nop 0
	s_nop 0
	s_nop 0
	v_add_f32_e32 v22, 1.0, v22
	v_cmp_gt_f32_e32 vcc, s35, v22
	s_nop 0
	s_nop 0
	v_cndmask_b32_e64 v24, 0, 32, vcc
	v_ldexp_f32 v22, v22, v24
	v_log_f32_e32 v22, v22
	v_cndmask_b32_e32 v24, 0, v186, vcc
	s_cmp_eq_u32 s0, 40
	v_add_u32_e32 v21, -8, v21
	v_mul_f32_e32 v25, 0x3f317217, v22
	v_fma_f32 v25, v22, s36, -v25
	v_fmac_f32_e32 v25, 0x3377d1cf, v22
	v_fmac_f32_e32 v25, 0x3f317217, v22
	v_cmp_lt_f32_e64 vcc, |v22|, s37
	v_lshl_add_u32 v40, v216, 1, 0
	s_nop 0
	v_cndmask_b32_e32 v22, v22, v25, vcc
	v_sub_f32_e32 v22, v22, v24
	v_sub_f32_e32 v22, v23, v22
	v_fmac_f32_e32 v20, 0x3d800000, v22
	v_mul_f32_e32 v22, 0x3fb8aa3b, v20
	v_mul_f32_e32 v23, 0xbfb8aa3b, v20
	v_exp_f32_e32 v22, v22
	v_exp_f32_e32 v23, v23
	s_nop 0
	s_nop 0
	v_mul_f32_e32 v22, v218, v22
	v_mul_f32_e32 v23, v23, v34
	v_bfe_u32 v24, v22, 16, 1
	v_bfe_u32 v25, v23, 16, 1
	v_add3_u32 v22, v22, v24, s38
	v_add3_u32 v23, v23, v25, s38
	ds_write_b16_d16_hi v201, v22
	ds_write_b16_d16_hi v201, v23 offset:34816
	s_nop 0
	s_nop 0
	s_nop 0
	ds_read_b128 v[48:51], v224
	ds_read_b128 v[52:55], v224 offset:32
	ds_read_b128 v[192:195], v224 offset:16
	ds_read_b128 v[196:199], v224 offset:48
	s_nop 0
	s_waitcnt lgkmcnt(3)
	v_mov_b32_e32 v190, v48
	s_waitcnt lgkmcnt(2)
	v_mov_b32_e32 v191, v52
	s_waitcnt lgkmcnt(1)
	v_mov_b32_e32 v200, v192
	s_waitcnt lgkmcnt(0)
	v_mov_b32_e32 v201, v196
	v_mov_b32_e32 v52, v49
	v_mov_b32_e32 v196, v193
	v_mov_b32_e32 v48, v50
	v_mov_b32_e32 v49, v54
	v_mov_b32_e32 v54, v51
	v_pk_fma_f32 v[50:51], v[0:1], v[190:191], v[16:17]
	v_pk_fma_f32 v[190:191], v[8:9], v[200:201], 0 op_sel_hi:[1,1,0]
	v_mov_b32_e32 v192, v194
	v_mov_b32_e32 v193, v198
	v_pk_fma_f32 v[50:51], v[2:3], v[52:53], v[50:51]
	v_pk_fma_f32 v[52:53], v[10:11], v[196:197], v[190:191]
	v_mov_b32_e32 v198, v195
	v_pk_fma_f32 v[48:49], v[4:5], v[48:49], v[50:51]
	v_pk_fma_f32 v[50:51], v[12:13], v[192:193], v[52:53]
	v_pk_fma_f32 v[48:49], v[6:7], v[54:55], v[48:49]
	v_pk_fma_f32 v[50:51], v[14:15], v[198:199], v[50:51]
	s_nop 0
	v_pk_add_f32 v[48:49], v[48:49], v[50:51]
	s_nop 0
	v_add_f32_e32 v48, v48, v49
	v_min_f32_e32 v49, 0, v48
	v_mul_f32_e64 v48, |v48|, s33
	v_exp_f32_e32 v48, v48
	s_nop 0
	v_add_f32_e32 v48, 1.0, v48
	v_cmp_gt_f32_e32 vcc, s35, v48
	s_nop 1
	v_cndmask_b32_e64 v50, 0, 32, vcc
	v_ldexp_f32 v48, v48, v50
	v_log_f32_e32 v48, v48
	v_cndmask_b32_e32 v50, 0, v186, vcc
	v_mul_f32_e32 v51, 0x3f317217, v48
	v_fma_f32 v51, v48, s36, -v51
	v_fmac_f32_e32 v51, 0x3377d1cf, v48
	v_fmac_f32_e32 v51, 0x3f317217, v48
	v_cmp_lt_f32_e64 vcc, |v48|, s37
	s_nop 1
	v_cndmask_b32_e32 v48, v48, v51, vcc
	v_sub_f32_e32 v48, v48, v50
	v_sub_f32_e32 v48, v49, v48
	v_fmac_f32_e32 v20, 0x3d800000, v48
	v_mul_f32_e32 v48, 0x3fb8aa3b, v20
	v_mul_f32_e32 v49, 0xbfb8aa3b, v20
	v_exp_f32_e32 v48, v48
	v_exp_f32_e32 v49, v49
	v_mul_f32_e32 v48, v219, v48
	v_mul_f32_e32 v38, v49, v38
	v_bfe_u32 v49, v48, 16, 1
	v_bfe_u32 v50, v38, 16, 1
	v_add3_u32 v48, v48, v49, s38
	v_add3_u32 v38, v38, v50, s38
	ds_write_b16_d16_hi v202, v48
	ds_write_b16_d16_hi v202, v38 offset:34816
	ds_read_b128 v[48:51], v225
	ds_read_b128 v[52:55], v225 offset:32
	ds_read_b128 v[192:195], v225 offset:16
	ds_read_b128 v[196:199], v225 offset:48
	s_waitcnt lgkmcnt(3)
	v_mov_b32_e32 v190, v48
	s_waitcnt lgkmcnt(2)
	v_mov_b32_e32 v191, v52
	s_waitcnt lgkmcnt(1)
	v_mov_b32_e32 v200, v192
	s_waitcnt lgkmcnt(0)
	v_mov_b32_e32 v201, v196
	v_mov_b32_e32 v52, v49
	v_mov_b32_e32 v196, v193
	v_mov_b32_e32 v48, v50
	v_mov_b32_e32 v49, v54
	v_mov_b32_e32 v54, v51
	v_pk_fma_f32 v[50:51], v[0:1], v[190:191], v[16:17]
	v_pk_fma_f32 v[190:191], v[8:9], v[200:201], 0 op_sel_hi:[1,1,0]
	v_mov_b32_e32 v192, v194
	v_mov_b32_e32 v193, v198
	v_pk_fma_f32 v[50:51], v[2:3], v[52:53], v[50:51]
	v_pk_fma_f32 v[52:53], v[10:11], v[196:197], v[190:191]
	v_mov_b32_e32 v198, v195
	v_pk_fma_f32 v[48:49], v[4:5], v[48:49], v[50:51]
	v_pk_fma_f32 v[50:51], v[12:13], v[192:193], v[52:53]
	v_pk_fma_f32 v[48:49], v[6:7], v[54:55], v[48:49]
	v_pk_fma_f32 v[50:51], v[14:15], v[198:199], v[50:51]
	s_nop 0
	v_pk_add_f32 v[48:49], v[48:49], v[50:51]
	s_nop 0
	v_add_f32_e32 v38, v48, v49
	v_min_f32_e32 v48, 0, v38
	v_mul_f32_e64 v38, |v38|, s33
	v_exp_f32_e32 v38, v38
	s_nop 0
	v_add_f32_e32 v38, 1.0, v38
	v_cmp_gt_f32_e32 vcc, s35, v38
	s_nop 1
	v_cndmask_b32_e64 v49, 0, 32, vcc
	v_ldexp_f32 v38, v38, v49
	v_log_f32_e32 v38, v38
	v_cndmask_b32_e32 v49, 0, v186, vcc
	v_mul_f32_e32 v50, 0x3f317217, v38
	v_fma_f32 v50, v38, s36, -v50
	v_fmac_f32_e32 v50, 0x3377d1cf, v38
	v_fmac_f32_e32 v50, 0x3f317217, v38
	v_cmp_lt_f32_e64 vcc, |v38|, s37
	s_nop 1
	v_cndmask_b32_e32 v38, v38, v50, vcc
	v_sub_f32_e32 v38, v38, v49
	v_sub_f32_e32 v38, v48, v38
	v_fmac_f32_e32 v20, 0x3d800000, v38
	v_mul_f32_e32 v38, 0x3fb8aa3b, v20
	v_mul_f32_e32 v48, 0xbfb8aa3b, v20
	v_exp_f32_e32 v38, v38
	v_exp_f32_e32 v48, v48
	v_mul_f32_e32 v38, v220, v38
	v_mul_f32_e32 v39, v48, v39
	v_bfe_u32 v48, v38, 16, 1
	v_bfe_u32 v49, v39, 16, 1
	v_add3_u32 v38, v38, v48, s38
	v_add3_u32 v39, v39, v49, s38
	ds_write_b16_d16_hi v204, v38
	ds_write_b16_d16_hi v204, v39 offset:34816
	ds_read_b128 v[48:51], v226
	ds_read_b128 v[52:55], v226 offset:32
	ds_read_b128 v[192:195], v226 offset:16
	ds_read_b128 v[196:199], v226 offset:48
	s_waitcnt lgkmcnt(3)
	v_mov_b32_e32 v38, v48
	s_waitcnt lgkmcnt(2)
	v_mov_b32_e32 v39, v52
	s_waitcnt lgkmcnt(1)
	v_mov_b32_e32 v190, v192
	s_waitcnt lgkmcnt(0)
	v_mov_b32_e32 v191, v196
	v_mov_b32_e32 v52, v49
	v_mov_b32_e32 v196, v193
	v_mov_b32_e32 v48, v50
	v_mov_b32_e32 v49, v54
	v_mov_b32_e32 v54, v51
	v_pk_fma_f32 v[38:39], v[0:1], v[38:39], v[16:17]
	v_pk_fma_f32 v[50:51], v[8:9], v[190:191], 0 op_sel_hi:[1,1,0]
	v_mov_b32_e32 v192, v194
	v_mov_b32_e32 v193, v198
	v_pk_fma_f32 v[38:39], v[2:3], v[52:53], v[38:39]
	v_pk_fma_f32 v[50:51], v[10:11], v[196:197], v[50:51]
	v_mov_b32_e32 v198, v195
	v_pk_fma_f32 v[38:39], v[4:5], v[48:49], v[38:39]
	v_pk_fma_f32 v[48:49], v[12:13], v[192:193], v[50:51]
	v_pk_fma_f32 v[38:39], v[6:7], v[54:55], v[38:39]
	v_pk_fma_f32 v[48:49], v[14:15], v[198:199], v[48:49]
	s_nop 0
	v_pk_add_f32 v[38:39], v[38:39], v[48:49]
	s_nop 0
	v_add_f32_e32 v38, v38, v39
	v_min_f32_e32 v39, 0, v38
	v_mul_f32_e64 v38, |v38|, s33
	v_exp_f32_e32 v38, v38
	s_nop 0
	v_add_f32_e32 v38, 1.0, v38
	v_cmp_gt_f32_e32 vcc, s35, v38
	s_nop 1
	v_cndmask_b32_e64 v48, 0, 32, vcc
	v_ldexp_f32 v38, v38, v48
	v_log_f32_e32 v38, v38
	v_cndmask_b32_e32 v48, 0, v186, vcc
	v_mul_f32_e32 v49, 0x3f317217, v38
	v_fma_f32 v49, v38, s36, -v49
	v_fmac_f32_e32 v49, 0x3377d1cf, v38
	v_fmac_f32_e32 v49, 0x3f317217, v38
	v_cmp_lt_f32_e64 vcc, |v38|, s37
	s_nop 1
	v_cndmask_b32_e32 v38, v38, v49, vcc
	v_sub_f32_e32 v38, v38, v48
	v_sub_f32_e32 v38, v39, v38
	v_fmac_f32_e32 v20, 0x3d800000, v38
	v_mul_f32_e32 v38, 0x3fb8aa3b, v20
	v_mul_f32_e32 v39, 0xbfb8aa3b, v20
	v_exp_f32_e32 v38, v38
	v_exp_f32_e32 v39, v39
	v_mul_f32_e32 v38, v221, v38
	v_mul_f32_e32 v39, v39, v41
	v_bfe_u32 v41, v38, 16, 1
	v_bfe_u32 v48, v39, 16, 1
	v_add3_u32 v38, v38, v41, s38
	v_add3_u32 v39, v39, v48, s38
	ds_write_b16_d16_hi v206, v38
	ds_write_b16_d16_hi v206, v39 offset:34816
	ds_read_b128 v[48:51], v227
	ds_read_b128 v[52:55], v227 offset:32
	ds_read_b128 v[192:195], v227 offset:16
	ds_read_b128 v[196:199], v227 offset:48
	s_waitcnt lgkmcnt(3)
	v_mov_b32_e32 v38, v48
	s_waitcnt lgkmcnt(2)
	v_mov_b32_e32 v39, v52
	s_waitcnt lgkmcnt(1)
	v_mov_b32_e32 v190, v192
	s_waitcnt lgkmcnt(0)
	v_mov_b32_e32 v191, v196
	v_mov_b32_e32 v52, v49
	v_mov_b32_e32 v196, v193
	v_mov_b32_e32 v48, v50
	v_mov_b32_e32 v49, v54
	v_mov_b32_e32 v54, v51
	v_pk_fma_f32 v[38:39], v[0:1], v[38:39], v[16:17]
	v_pk_fma_f32 v[50:51], v[8:9], v[190:191], 0 op_sel_hi:[1,1,0]
	v_mov_b32_e32 v192, v194
	v_mov_b32_e32 v193, v198
	v_pk_fma_f32 v[38:39], v[2:3], v[52:53], v[38:39]
	v_pk_fma_f32 v[50:51], v[10:11], v[196:197], v[50:51]
	v_mov_b32_e32 v198, v195
	v_pk_fma_f32 v[38:39], v[4:5], v[48:49], v[38:39]
	v_pk_fma_f32 v[48:49], v[12:13], v[192:193], v[50:51]
	v_pk_fma_f32 v[38:39], v[6:7], v[54:55], v[38:39]
	v_pk_fma_f32 v[48:49], v[14:15], v[198:199], v[48:49]
	s_nop 0
	v_pk_add_f32 v[38:39], v[38:39], v[48:49]
	s_nop 0
	v_add_f32_e32 v38, v38, v39
	v_min_f32_e32 v39, 0, v38
	v_mul_f32_e64 v38, |v38|, s33
	v_exp_f32_e32 v38, v38
	s_nop 0
	v_add_f32_e32 v38, 1.0, v38
	v_cmp_gt_f32_e32 vcc, s35, v38
	s_nop 1
	v_cndmask_b32_e64 v41, 0, 32, vcc
	v_ldexp_f32 v38, v38, v41
	v_log_f32_e32 v38, v38
	v_cndmask_b32_e32 v41, 0, v186, vcc
	v_mul_f32_e32 v48, 0x3f317217, v38
	v_fma_f32 v48, v38, s36, -v48
	v_fmac_f32_e32 v48, 0x3377d1cf, v38
	v_fmac_f32_e32 v48, 0x3f317217, v38
	v_cmp_lt_f32_e64 vcc, |v38|, s37
	s_nop 1
	v_cndmask_b32_e32 v38, v38, v48, vcc
	v_sub_f32_e32 v38, v38, v41
	v_sub_f32_e32 v38, v39, v38
	v_fmac_f32_e32 v20, 0x3d800000, v38
	v_mul_f32_e32 v38, 0x3fb8aa3b, v20
	v_mul_f32_e32 v39, 0xbfb8aa3b, v20
	v_exp_f32_e32 v38, v38
	v_exp_f32_e32 v39, v39
	v_mul_f32_e32 v38, v222, v38
	v_mul_f32_e32 v39, v39, v42
	v_bfe_u32 v41, v38, 16, 1
	v_bfe_u32 v42, v39, 16, 1
	v_add3_u32 v38, v38, v41, s38
	v_add3_u32 v39, v39, v42, s38
	ds_write_b16_d16_hi v208, v38
	ds_write_b16_d16_hi v208, v39 offset:34816
	ds_read_b128 v[48:51], v228
	ds_read_b128 v[52:55], v228 offset:32
	ds_read_b128 v[192:195], v228 offset:16
	ds_read_b128 v[196:199], v228 offset:48
	s_waitcnt lgkmcnt(3)
	v_mov_b32_e32 v38, v48
	s_waitcnt lgkmcnt(2)
	v_mov_b32_e32 v39, v52
	s_waitcnt lgkmcnt(1)
	v_mov_b32_e32 v190, v192
	s_waitcnt lgkmcnt(0)
	v_mov_b32_e32 v191, v196
	v_mov_b32_e32 v52, v49
	v_mov_b32_e32 v196, v193
	v_mov_b32_e32 v48, v50
	v_mov_b32_e32 v49, v54
	v_mov_b32_e32 v54, v51
	v_pk_fma_f32 v[38:39], v[0:1], v[38:39], v[16:17]
	v_pk_fma_f32 v[50:51], v[8:9], v[190:191], 0 op_sel_hi:[1,1,0]
	v_mov_b32_e32 v192, v194
	v_mov_b32_e32 v193, v198
	v_pk_fma_f32 v[38:39], v[2:3], v[52:53], v[38:39]
	v_pk_fma_f32 v[50:51], v[10:11], v[196:197], v[50:51]
	v_mov_b32_e32 v198, v195
	v_pk_fma_f32 v[38:39], v[4:5], v[48:49], v[38:39]
	v_pk_fma_f32 v[48:49], v[12:13], v[192:193], v[50:51]
	v_pk_fma_f32 v[38:39], v[6:7], v[54:55], v[38:39]
	v_pk_fma_f32 v[48:49], v[14:15], v[198:199], v[48:49]
	s_nop 0
	v_pk_add_f32 v[38:39], v[38:39], v[48:49]
	s_nop 0
	v_add_f32_e32 v38, v38, v39
	v_min_f32_e32 v39, 0, v38
	v_mul_f32_e64 v38, |v38|, s33
	v_exp_f32_e32 v38, v38
	s_nop 0
	v_add_f32_e32 v38, 1.0, v38
	v_cmp_gt_f32_e32 vcc, s35, v38
	s_nop 1
	v_cndmask_b32_e64 v41, 0, 32, vcc
	v_ldexp_f32 v38, v38, v41
	v_log_f32_e32 v38, v38
	v_cndmask_b32_e32 v41, 0, v186, vcc
	v_mul_f32_e32 v42, 0x3f317217, v38
	v_fma_f32 v42, v38, s36, -v42
	v_fmac_f32_e32 v42, 0x3377d1cf, v38
	v_fmac_f32_e32 v42, 0x3f317217, v38
	v_cmp_lt_f32_e64 vcc, |v38|, s37
	s_nop 1
	v_cndmask_b32_e32 v38, v38, v42, vcc
	v_sub_f32_e32 v38, v38, v41
	v_sub_f32_e32 v38, v39, v38
	v_fmac_f32_e32 v20, 0x3d800000, v38
	v_mul_f32_e32 v38, 0x3fb8aa3b, v20
	v_mul_f32_e32 v39, 0xbfb8aa3b, v20
	v_exp_f32_e32 v38, v38
	v_exp_f32_e32 v39, v39
	v_mul_f32_e32 v38, v47, v38
	v_mul_f32_e32 v39, v39, v44
	v_bfe_u32 v41, v38, 16, 1
	v_bfe_u32 v42, v39, 16, 1
	v_add3_u32 v38, v38, v41, s38
	v_add3_u32 v39, v39, v42, s38
	ds_write_b16_d16_hi v209, v38
	ds_write_b16_d16_hi v209, v39 offset:34816
	ds_read_b128 v[48:51], v43
	ds_read_b128 v[52:55], v43 offset:32
	ds_read_b128 v[192:195], v43 offset:16
	ds_read_b128 v[196:199], v43 offset:48
	s_waitcnt lgkmcnt(3)
	v_mov_b32_e32 v38, v48
	s_waitcnt lgkmcnt(2)
	v_mov_b32_e32 v39, v52
	s_waitcnt lgkmcnt(1)
	v_mov_b32_e32 v42, v192
	s_waitcnt lgkmcnt(0)
	v_mov_b32_e32 v43, v196
	v_mov_b32_e32 v52, v49
	v_mov_b32_e32 v196, v193
	v_pk_fma_f32 v[38:39], v[0:1], v[38:39], v[16:17]
	v_pk_fma_f32 v[42:43], v[8:9], v[42:43], 0 op_sel_hi:[1,1,0]
	v_mov_b32_e32 v48, v50
	v_mov_b32_e32 v49, v54
	v_mov_b32_e32 v190, v194
	v_mov_b32_e32 v191, v198
	v_pk_fma_f32 v[38:39], v[2:3], v[52:53], v[38:39]
	v_pk_fma_f32 v[42:43], v[10:11], v[196:197], v[42:43]
	v_mov_b32_e32 v54, v51
	v_mov_b32_e32 v198, v195
	v_pk_fma_f32 v[38:39], v[4:5], v[48:49], v[38:39]
	v_pk_fma_f32 v[42:43], v[12:13], v[190:191], v[42:43]
	v_pk_fma_f32 v[38:39], v[6:7], v[54:55], v[38:39]
	v_pk_fma_f32 v[42:43], v[14:15], v[198:199], v[42:43]
	s_nop 0
	v_pk_add_f32 v[38:39], v[38:39], v[42:43]
	s_nop 0
	v_add_f32_e32 v38, v38, v39
	v_min_f32_e32 v39, 0, v38
	v_mul_f32_e64 v38, |v38|, s33
	v_exp_f32_e32 v38, v38
	s_nop 0
	v_add_f32_e32 v38, 1.0, v38
	v_cmp_gt_f32_e32 vcc, s35, v38
	s_nop 1
	v_cndmask_b32_e64 v41, 0, 32, vcc
	v_ldexp_f32 v38, v38, v41
	v_log_f32_e32 v38, v38
	v_cndmask_b32_e32 v41, 0, v186, vcc
	v_mul_f32_e32 v42, 0x3f317217, v38
	v_fma_f32 v42, v38, s36, -v42
	v_fmac_f32_e32 v42, 0x3377d1cf, v38
	v_fmac_f32_e32 v42, 0x3f317217, v38
	v_cmp_lt_f32_e64 vcc, |v38|, s37
	s_nop 1
	v_cndmask_b32_e32 v38, v38, v42, vcc
	v_sub_f32_e32 v38, v38, v41
	v_sub_f32_e32 v38, v39, v38
	v_fmac_f32_e32 v20, 0x3d800000, v38
	v_mul_f32_e32 v38, 0x3fb8aa3b, v20
	v_mul_f32_e32 v39, 0xbfb8aa3b, v20
	v_exp_f32_e32 v38, v38
	v_exp_f32_e32 v39, v39
	v_mul_f32_e32 v38, v45, v38
	v_mul_f32_e32 v39, v39, v46
	v_bfe_u32 v41, v38, 16, 1
	v_bfe_u32 v42, v39, 16, 1
	v_add3_u32 v38, v38, v41, s38
	v_add3_u32 v39, v39, v42, s38
	ds_write_b16_d16_hi v40, v38
	ds_write_b16_d16_hi v40, v39 offset:34816
	s_waitcnt vmcnt(0)
	v_mov_b32_e32 v36, v229
	v_mov_b32_e32 v37, v230
	v_mov_b32_e32 v34, v231
	v_mov_b32_e32 v35, v232
	v_mov_b32_e32 v32, v233
	v_mov_b32_e32 v33, v234
	v_mov_b32_e32 v30, v235
	v_mov_b32_e32 v31, v236
	v_mov_b32_e32 v28, v237
	v_mov_b32_e32 v29, v238
	v_mov_b32_e32 v26, v239
	v_mov_b32_e32 v27, v240
	v_mov_b32_e32 v24, v241
	v_mov_b32_e32 v25, v242
	v_mov_b32_e32 v22, v243
	v_mov_b32_e32 v23, v244
	s_cbranch_scc0 .LBB0_764
	s_mov_b32 s0, 0
	s_mov_b64 s[10:11], -1
	s_waitcnt lgkmcnt(0)
	s_barrier
	s_branch .LBB0_767
